# v36: v25 + conv tap loop 8 rows per pass + epilogue stores deferred two sites + accumulators cleared with v_mov_b64
# speedup vs baseline: 1.0089x; 1.0045x over previous
; template <class Epi, class Sched, bool ALIGN_EPI = false, bool SP2 = false>
; __device__ __forceinline__ void gemm_phase(PG8_LAS unsigned char* lds, const Gemm g, const Sched& S, const Epi& E, const int tid) {
;     ...
;         const bool has_next = S.next(ui + 1, nxt);
;         const char* nA = has_next ? (const char*)g.A + (size_t)(nxt.pm >> 3) * g.gsa + (size_t)(nxt.pm & 7) * tstepA : cA; const char* nB = has_next ? (const char*)g.Bt + (size_t)nxt.pn * tstepB : cB;
;     ...
; #pragma unroll
;         for (int a = 0; a < 2; ++a)
; #pragma unroll
;             for (int b = 0; b < 2; ++b)
; #pragma unroll
;                 for (int m = 0; m < 4; ++m)
; #pragma unroll
;                     for (int n = 0; n < 2; ++n) acc[a][b][m][n] = (f32x4){0.f, 0.f, 0.f, 0.f};
.LBB0_34:
	s_ashr_i32 s14, s21, 3
	s_ashr_i32 s15, s14, 31
	v_readlane_b32 s44, v253, 57
	s_lshl_b64 s[14:15], s[14:15], 23
	v_readlane_b32 s58, v254, 7
	v_readlane_b32 s59, v254, 8
	s_add_u32 s13, s58, s14
	s_addc_u32 s15, s59, s15
	s_lshl_b32 s14, s21, 20
	s_and_b32 s14, s14, 0x700000
	s_add_u32 s14, s13, s14
	s_addc_u32 s15, s15, 0
	s_and_b64 s[16:17], s[6:7], exec
	s_cselect_b32 s26, s15, s9
	s_cselect_b32 s27, s14, s8
	s_ashr_i32 s13, s12, 31
	s_lshl_b64 s[16:17], s[12:13], 19
	s_add_u32 s16, s0, s16
	s_addc_u32 s17, s1, s17
	s_and_b64 s[22:23], s[6:7], exec
	s_cselect_b32 s13, s17, s19
	s_cselect_b32 s28, s16, s18
	s_add_u32 s8, s8, 0x80080
	s_addc_u32 s9, s9, 0
	s_add_u32 s29, s18, 0x100
	s_addc_u32 s30, s19, 0
	s_mov_b32 s31, -2
	v_mov_b64_e32 v[0:1], 0
	v_mov_b64_e32 v[2:3], 0
	v_mov_b64_e32 v[4:5], 0
	v_mov_b64_e32 v[6:7], 0
	v_mov_b64_e32 v[8:9], 0
	v_mov_b64_e32 v[10:11], 0
	v_mov_b64_e32 v[12:13], 0
	v_mov_b64_e32 v[14:15], 0
	v_mov_b64_e32 v[16:17], 0
	v_mov_b64_e32 v[18:19], 0
	v_mov_b64_e32 v[20:21], 0
	v_mov_b64_e32 v[22:23], 0
	v_mov_b64_e32 v[24:25], 0
	v_mov_b64_e32 v[26:27], 0
	v_mov_b64_e32 v[28:29], 0
	v_mov_b64_e32 v[30:31], 0
	v_mov_b64_e32 v[32:33], 0
	v_mov_b64_e32 v[34:35], 0
	v_mov_b64_e32 v[36:37], 0
	v_mov_b64_e32 v[38:39], 0
	v_mov_b64_e32 v[40:41], 0
	v_mov_b64_e32 v[42:43], 0
	v_mov_b64_e32 v[44:45], 0
	v_mov_b64_e32 v[46:47], 0
	v_mov_b64_e32 v[48:49], 0
	v_mov_b64_e32 v[50:51], 0
	v_mov_b64_e32 v[52:53], 0
	v_mov_b64_e32 v[54:55], 0
	v_mov_b64_e32 v[56:57], 0
	v_mov_b64_e32 v[58:59], 0
	v_mov_b64_e32 v[60:61], 0
	v_mov_b64_e32 v[62:63], 0
	v_mov_b64_e32 v[64:65], 0
	v_mov_b64_e32 v[66:67], 0
	v_mov_b64_e32 v[68:69], 0
	v_mov_b64_e32 v[70:71], 0
	v_mov_b64_e32 v[72:73], 0
	v_mov_b64_e32 v[74:75], 0
	v_mov_b64_e32 v[76:77], 0
	v_mov_b64_e32 v[78:79], 0
	v_mov_b64_e32 v[80:81], 0
	v_mov_b64_e32 v[82:83], 0
	v_mov_b64_e32 v[84:85], 0
	v_mov_b64_e32 v[86:87], 0
	v_mov_b64_e32 v[88:89], 0
	v_mov_b64_e32 v[90:91], 0
	v_mov_b64_e32 v[92:93], 0
	v_mov_b64_e32 v[94:95], 0
	v_mov_b64_e32 v[96:97], 0
	v_mov_b64_e32 v[98:99], 0
	v_mov_b64_e32 v[100:101], 0
	v_mov_b64_e32 v[102:103], 0
	v_mov_b64_e32 v[104:105], 0
	v_mov_b64_e32 v[106:107], 0
	v_mov_b64_e32 v[108:109], 0
	v_mov_b64_e32 v[110:111], 0
	v_mov_b64_e32 v[112:113], 0
	v_mov_b64_e32 v[114:115], 0
	v_mov_b64_e32 v[116:117], 0
	v_mov_b64_e32 v[118:119], 0
	v_mov_b64_e32 v[120:121], 0
	v_mov_b64_e32 v[122:123], 0
	v_mov_b64_e32 v[124:125], 0
	v_mov_b64_e32 v[126:127], 0
	v_readlane_b32 s45, v253, 58
	v_readlane_b32 s46, v253, 59
	v_readlane_b32 s47, v253, 60
	v_readlane_b32 s48, v253, 61
	v_readlane_b32 s49, v253, 62
	v_readlane_b32 s50, v253, 63
	v_readlane_b32 s51, v254, 0
	v_readlane_b32 s52, v254, 1
	v_readlane_b32 s53, v254, 2
	v_readlane_b32 s54, v254, 3
	v_readlane_b32 s55, v254, 4
	v_readlane_b32 s56, v254, 5
	v_readlane_b32 s57, v254, 6

; template <class Epi, class Sched, bool ALIGN_EPI = false, bool SP2 = false>
; __device__ __forceinline__ void gemm_phase(PG8_LAS unsigned char* lds, const Gemm g, const Sched& S, const Epi& E, const int tid) {
;     ...
;         const bool has_next = S.next(ui + 1, nxt);
;         const char* nA = has_next ? (const char*)g.A + (size_t)(nxt.pm >> 3) * g.gsa + (size_t)(nxt.pm & 7) * tstepA : cA; const char* nB = has_next ? (const char*)g.Bt + (size_t)nxt.pn * tstepB : cB;
;     ...
; #pragma unroll
;         for (int a = 0; a < 2; ++a)
; #pragma unroll
;             for (int b = 0; b < 2; ++b)
; #pragma unroll
;                 for (int m = 0; m < 4; ++m)
; #pragma unroll
;                     for (int n = 0; n < 2; ++n) acc[a][b][m][n] = (f32x4){0.f, 0.f, 0.f, 0.f};
.LBB0_467:
	s_ashr_i32 s71, s70, 31
	s_lshl_b64 s[42:43], s[70:71], s97
	s_add_u32 s86, s10, s42
	s_addc_u32 s87, s11, s43
	s_and_b64 s[8:9], s[8:9], exec
	s_cselect_b32 s42, s87, s93
	s_cselect_b32 s43, s86, s92
	s_add_u32 s8, s94, 0x80
	s_addc_u32 s9, s95, 0
	s_add_u32 s44, s92, 0x100
	s_addc_u32 s45, s93, 0
	s_mov_b32 s46, 0
	v_mov_b64_e32 v[0:1], 0
	v_mov_b64_e32 v[2:3], 0
	v_mov_b64_e32 v[4:5], 0
	v_mov_b64_e32 v[6:7], 0
	v_mov_b64_e32 v[8:9], 0
	v_mov_b64_e32 v[10:11], 0
	v_mov_b64_e32 v[12:13], 0
	v_mov_b64_e32 v[14:15], 0
	v_mov_b64_e32 v[16:17], 0
	v_mov_b64_e32 v[18:19], 0
	v_mov_b64_e32 v[20:21], 0
	v_mov_b64_e32 v[22:23], 0
	v_mov_b64_e32 v[24:25], 0
	v_mov_b64_e32 v[26:27], 0
	v_mov_b64_e32 v[28:29], 0
	v_mov_b64_e32 v[30:31], 0
	v_mov_b64_e32 v[32:33], 0
	v_mov_b64_e32 v[34:35], 0
	v_mov_b64_e32 v[36:37], 0
	v_mov_b64_e32 v[38:39], 0
	v_mov_b64_e32 v[40:41], 0
	v_mov_b64_e32 v[42:43], 0
	v_mov_b64_e32 v[44:45], 0
	v_mov_b64_e32 v[46:47], 0
	v_mov_b64_e32 v[48:49], 0
	v_mov_b64_e32 v[50:51], 0
	v_mov_b64_e32 v[52:53], 0
	v_mov_b64_e32 v[54:55], 0
	v_mov_b64_e32 v[56:57], 0
	v_mov_b64_e32 v[58:59], 0
	v_mov_b64_e32 v[60:61], 0
	v_mov_b64_e32 v[62:63], 0
	v_mov_b64_e32 v[64:65], 0
	v_mov_b64_e32 v[66:67], 0
	v_mov_b64_e32 v[68:69], 0
	v_mov_b64_e32 v[70:71], 0
	v_mov_b64_e32 v[72:73], 0
	v_mov_b64_e32 v[74:75], 0
	v_mov_b64_e32 v[76:77], 0
	v_mov_b64_e32 v[78:79], 0
	v_mov_b64_e32 v[80:81], 0
	v_mov_b64_e32 v[82:83], 0
	v_mov_b64_e32 v[84:85], 0
	v_mov_b64_e32 v[86:87], 0
	v_mov_b64_e32 v[88:89], 0
	v_mov_b64_e32 v[90:91], 0
	v_mov_b64_e32 v[92:93], 0
	v_mov_b64_e32 v[94:95], 0
	v_mov_b64_e32 v[96:97], 0
	v_mov_b64_e32 v[98:99], 0
	v_mov_b64_e32 v[100:101], 0
	v_mov_b64_e32 v[102:103], 0
	v_mov_b64_e32 v[104:105], 0
	v_mov_b64_e32 v[106:107], 0
	v_mov_b64_e32 v[108:109], 0
	v_mov_b64_e32 v[110:111], 0
	v_mov_b64_e32 v[112:113], 0
	v_mov_b64_e32 v[114:115], 0
	v_mov_b64_e32 v[116:117], 0
	v_mov_b64_e32 v[118:119], 0
	v_mov_b64_e32 v[120:121], 0
	v_mov_b64_e32 v[122:123], 0
	v_mov_b64_e32 v[124:125], 0
	v_mov_b64_e32 v[126:127], 0
